# GEMM phases: first K-iteration of each later unit waits with counts that do not include the epilogue stores (vmcnt 24 / none), stray vmcnt(0) at out-proj unit top removed
# baseline (speedup 1.0000x reference)
;     __host__ __device__ bool next(int i, Unit& u) const {
;         const int per = (nwg + G - 1) / G; if (i >= per * rep) return false; const long L = (long)(i % per) * G + c; if (L >= nwg) return false;
;         int wgid = (int)L; { const int q = nwg / NXCD, r = nwg % NXCD, xcd = wgid % NXCD, off = wgid / NXCD; wgid = (xcd < r ? xcd * (q + 1) : r * (q + 1) + (xcd - r) * q) + off; }
;         const int nig = WGM * nN, gid = wgid / nig, fm = gid * WGM, gsz = (nM - fm) < WGM ? (nM - fm) : WGM;
;         u.pm = fm + ((wgid % nig) % gsz); u.pn = (wgid % nig) / gsz; return true;
; template <class Epi, class Sched, bool ALIGN_EPI = false, bool SP2 = false>
; __device__ __forceinline__ void gemm_phase(PG8_LAS unsigned char* lds, const Gemm g, const Sched& S, const Epi& E) {
;     ...
;     if (!S.next(0, cur)) return;
.LBB0_146:
	s_or_b64 exec, exec, s[0:1]
	s_abs_i32 s83, s54
	s_waitcnt lgkmcnt(0)
	v_cvt_f32_u32_e32 v0, s83
	s_add_i32 s0, s54, 0x17ff
	s_sub_i32 s4, 0xffffe801, s54
	s_ashr_i32 s1, s0, 31
	v_rcp_iflag_f32_e32 v0, v0
	s_max_i32 s0, s0, s4
	s_sub_i32 s4, 0, s83
	s_ashr_i32 s82, s54, 31
	v_mul_f32_e32 v0, 0x4f7ffffe, v0
	v_cvt_u32_f32_e32 v0, v0
	s_xor_b32 s1, s1, s82
	v_readfirstlane_b32 s8, v178
	v_readfirstlane_b32 s84, v0
	s_mul_i32 s4, s4, s84
	s_mul_hi_u32 s4, s84, s4
	s_add_i32 s84, s84, s4
	s_mul_hi_u32 s4, s0, s84
	s_mul_i32 s5, s4, s83
	s_sub_i32 s0, s0, s5
	s_add_i32 s5, s4, 1
	s_sub_i32 s6, s0, s83
	s_cmp_ge_u32 s0, s83
	s_cselect_b32 s4, s5, s4
	s_cselect_b32 s0, s6, s0
	s_add_i32 s5, s4, 1
	s_cmp_ge_u32 s0, s83
	s_cselect_b32 s0, s5, s4
	s_xor_b32 s0, s0, s1
	s_sub_i32 s68, s0, s1
	s_cmp_gt_i32 s68, 0
	s_cselect_b64 s[0:1], -1, 0
	s_cmpk_lt_i32 s2, 0x1800
	s_cselect_b64 s[4:5], -1, 0
	s_and_b64 s[4:5], s[4:5], s[0:1]
	v_cndmask_b32_e64 v0, 0, 1, s[4:5]
	v_cmp_ne_u32_e64 s[0:1], 1, v0
	s_andn2_b64 vcc, exec, s[4:5]
	s_barrier
	s_mov_b32 s95, 0
	s_cbranch_vccnz .LBB0_148
	s_ashr_i32 s4, s2, 31
	s_lshr_b32 s4, s4, 29
	s_add_i32 s4, s2, s4
	s_ashr_i32 s5, s4, 3
	s_and_b32 s4, s4, -8
	s_sub_i32 s4, s2, s4
	s_cmp_lt_i32 s4, 0
	s_movk_i32 s6, 0x301
	s_cselect_b32 s6, s6, 0x300
	s_mul_i32 s4, s4, s6
	s_add_i32 s4, s4, s5
	s_mul_hi_i32 s5, s4, 0x2aaaaaab
	s_lshr_b32 s6, s5, 31
	s_ashr_i32 s5, s5, 5
	s_add_i32 s5, s5, s6
	s_lshl_b32 s6, s5, 3
	s_mulk_i32 s5, 0xc0
	s_sub_i32 s4, s4, s5
	s_sext_i32_i16 s5, s4
	s_bfe_u32 s5, s5, 0x3001c
	s_add_i32 s5, s4, s5
	s_sext_i32_i16 s7, s5
	s_and_b32 s5, s5, 0xfff8
	s_sub_i32 s4, s4, s5
	s_sext_i32_i16 s4, s4
	s_add_i32 s6, s6, s4
	s_ashr_i32 s4, s7, 3

; #define PG8_STAGE(bufoff, gbase, voff) do { _Pragma("unroll") for (int _i = 0; _i < 2; ++_i) \
;         __builtin_amdgcn_global_load_lds((const unsigned*)((const char*)(gbase) + (voff)[_i]), (PG8_LAS unsigned*)(lds + (bufoff) + ldsw + _i * 8192), 16, 0, 0); } while (0)
; #define PG8_LDA(dst, b, h) do { _Pragma("unroll") for (int m = 0; m < 4; ++m) _Pragma("unroll") for (int k = 0; k < 2; ++k) dst[m][k] = *(const PG8_LAS bf16x8*)(lds + PG8_SA(b, h) + aoff + m * 2048 + k * 1024); } while (0)
; #define PG8_LDB(dst, b, h) do { _Pragma("unroll") for (int n = 0; n < 2; ++n) _Pragma("unroll") for (int k = 0; k < 2; ++k) dst[n][k] = *(const PG8_LAS bf16x8*)(lds + PG8_SB(b, h) + boff + n * 2048 + k * 1024); } while (0)
; #define PG8_WAIT_V(n) asm volatile("s_waitcnt vmcnt(" #n ")" ::: "memory")
; #define PG8_WAIT_L(n) asm volatile("s_waitcnt lgkmcnt(" #n ")" ::: "memory")
; #define PG8_BAR __builtin_amdgcn_s_barrier()
; template <class Epi, class Sched, bool ALIGN_EPI = false, bool SP2 = false>
; __device__ __forceinline__ void gemm_phase(PG8_LAS unsigned char* lds, const Gemm g, const Sched& S, const Epi& E) {
;     ...
;         const bool has_next = S.next(ui + 1, nxt);
;         const char* nA = has_next ? (const char*)g.A + (size_t)nxt.pm * tstep : cA; const char* nB = has_next ? (const char*)g.Bt + (size_t)nxt.pn * tstep : cB;
;         for (int t = 0; t < nt; t += 2) {
;             const bool last = (t == nt - 2);
;             const char* a1 = cA + (size_t)(t + 1) * kstep;
;             const char* a2 = last ? nA : cA + (size_t)(t + 2) * kstep; const char* b2 = last ? nB : cB + (size_t)(t + 2) * kstep;
;             const char* a3 = a2 + kstep; const char* b3 = b2 + kstep;
;             if (last && has_next) S.a_ready(nxt);
;             if constexpr (SP2) {
;             PG8_LDB(B0, 0, 0); PG8_LDB(B1, 0, 1); PG8_SCHED; PG8_LDA(At, 0, 0); PG8_STAGE(PG8_SA(1, 1), a1 + hstep, voffA);
;             PG8_WAIT_V(8); PG8_WAIT_L(0); PG8_BAR; PG8_MMA(0, 0, At, B0); PG8_MMA(0, 1, At, B1); PG8_BAR; PG8_SCHED;
;     ...
; #pragma unroll
;         for (int a = 0; a < 2; ++a)
; #pragma unroll
;             for (int b = 0; b < 2; ++b)
; #pragma unroll
;                 for (int m = 0; m < 4; ++m)
; #pragma unroll
;                     for (int n = 0; n < 2; ++n) acc[a][b][m][n] = (f32x4){0.f, 0.f, 0.f, 0.f};
;         cur = nxt; cA = nA; cB = nB; ++ui;
.LBB0_157:
	s_ashr_i32 s21, s20, 31
	s_lshl_b64 s[24:25], s[20:21], 19
	s_add_u32 s24, s46, s24
	s_addc_u32 s25, s47, s25
	s_and_b64 s[26:27], s[22:23], exec
	s_cselect_b32 s5, s25, s29
	s_cselect_b32 s7, s24, s28
	s_ashr_i32 s17, s16, 31
	s_lshl_b64 s[26:27], s[16:17], 19
	s_add_u32 s26, s52, s26
	s_addc_u32 s27, s53, s27
	s_and_b64 s[60:61], s[22:23], exec
	s_cselect_b32 s8, s27, s59
	s_cselect_b32 s17, s26, s58
	s_add_u32 s28, s28, 0x40080
	s_addc_u32 s29, s29, 0
	s_add_u32 s21, s58, 0x100
	v_mov_b32_e32 v0, 0
	s_addc_u32 s62, s59, 0
	s_mov_b32 s63, -2
	s_mov_b32 s96, s95
	s_mov_b32 s95, 1
	v_mov_b32_e32 v1, v0
	v_mov_b32_e32 v2, v0
	v_mov_b32_e32 v3, v0
	v_mov_b32_e32 v4, v0
	v_mov_b32_e32 v5, v0
	v_mov_b32_e32 v6, v0
	v_mov_b32_e32 v7, v0
	v_mov_b32_e32 v16, v0
	v_mov_b32_e32 v17, v0
	v_mov_b32_e32 v18, v0
	v_mov_b32_e32 v19, v0
	v_mov_b32_e32 v20, v0
	v_mov_b32_e32 v21, v0
	v_mov_b32_e32 v22, v0
	v_mov_b32_e32 v23, v0
	v_mov_b32_e32 v32, v0
	v_mov_b32_e32 v33, v0
	v_mov_b32_e32 v34, v0
	v_mov_b32_e32 v35, v0
	v_mov_b32_e32 v36, v0
	v_mov_b32_e32 v37, v0
	v_mov_b32_e32 v38, v0
	v_mov_b32_e32 v39, v0
	v_mov_b32_e32 v48, v0
	v_mov_b32_e32 v49, v0
	v_mov_b32_e32 v50, v0
	v_mov_b32_e32 v51, v0
	v_mov_b32_e32 v52, v0
	v_mov_b32_e32 v53, v0
	v_mov_b32_e32 v54, v0
	v_mov_b32_e32 v55, v0
	v_mov_b32_e32 v8, v0
	v_mov_b32_e32 v9, v0
	v_mov_b32_e32 v10, v0
	v_mov_b32_e32 v11, v0
	v_mov_b32_e32 v12, v0
	v_mov_b32_e32 v13, v0
	v_mov_b32_e32 v14, v0
	v_mov_b32_e32 v15, v0
	v_mov_b32_e32 v24, v0
	v_mov_b32_e32 v25, v0
	v_mov_b32_e32 v26, v0
	v_mov_b32_e32 v27, v0
	v_mov_b32_e32 v28, v0
	v_mov_b32_e32 v29, v0
	v_mov_b32_e32 v30, v0
	v_mov_b32_e32 v31, v0
	v_mov_b32_e32 v40, v0
	v_mov_b32_e32 v41, v0
	v_mov_b32_e32 v42, v0
	v_mov_b32_e32 v43, v0
	v_mov_b32_e32 v44, v0
	v_mov_b32_e32 v45, v0
	v_mov_b32_e32 v46, v0
	v_mov_b32_e32 v47, v0
	v_mov_b32_e32 v56, v0
	v_mov_b32_e32 v57, v0
	v_mov_b32_e32 v58, v0
	v_mov_b32_e32 v59, v0
	v_mov_b32_e32 v60, v0
	v_mov_b32_e32 v61, v0
	v_mov_b32_e32 v62, v0
	v_mov_b32_e32 v63, v0
	v_mov_b32_e32 v64, v0
	v_mov_b32_e32 v65, v0
	v_mov_b32_e32 v66, v0
	v_mov_b32_e32 v67, v0
	v_mov_b32_e32 v68, v0
	v_mov_b32_e32 v69, v0
	v_mov_b32_e32 v70, v0
	v_mov_b32_e32 v71, v0
	v_mov_b32_e32 v80, v0
	v_mov_b32_e32 v81, v0
	v_mov_b32_e32 v82, v0
	v_mov_b32_e32 v83, v0
	v_mov_b32_e32 v84, v0
	v_mov_b32_e32 v85, v0
	v_mov_b32_e32 v86, v0
	v_mov_b32_e32 v87, v0
	v_mov_b32_e32 v96, v0
	v_mov_b32_e32 v97, v0
	v_mov_b32_e32 v98, v0
	v_mov_b32_e32 v99, v0
	v_mov_b32_e32 v100, v0
	v_mov_b32_e32 v101, v0
	v_mov_b32_e32 v102, v0
	v_mov_b32_e32 v103, v0
	v_mov_b32_e32 v112, v0
	v_mov_b32_e32 v113, v0
	v_mov_b32_e32 v114, v0
	v_mov_b32_e32 v115, v0
	v_mov_b32_e32 v116, v0
	v_mov_b32_e32 v117, v0
	v_mov_b32_e32 v118, v0
	v_mov_b32_e32 v119, v0
	v_mov_b32_e32 v72, v0
	v_mov_b32_e32 v73, v0
	v_mov_b32_e32 v74, v0
	v_mov_b32_e32 v75, v0
	v_mov_b32_e32 v76, v0
	v_mov_b32_e32 v77, v0
	v_mov_b32_e32 v78, v0
	v_mov_b32_e32 v79, v0
	v_mov_b32_e32 v88, v0
	v_mov_b32_e32 v89, v0
	v_mov_b32_e32 v90, v0
	v_mov_b32_e32 v91, v0
	v_mov_b32_e32 v92, v0
	v_mov_b32_e32 v93, v0
	v_mov_b32_e32 v94, v0
	v_mov_b32_e32 v95, v0
	v_mov_b32_e32 v104, v0
	v_mov_b32_e32 v105, v0
	v_mov_b32_e32 v106, v0
	v_mov_b32_e32 v107, v0
	v_mov_b32_e32 v108, v0
	v_mov_b32_e32 v109, v0
	v_mov_b32_e32 v110, v0
	v_mov_b32_e32 v111, v0
	v_mov_b32_e32 v120, v0
	v_mov_b32_e32 v121, v0
	v_mov_b32_e32 v122, v0
	v_mov_b32_e32 v123, v0
	v_mov_b32_e32 v124, v0
	v_mov_b32_e32 v125, v0
	v_mov_b32_e32 v126, v0
	v_mov_b32_e32 v127, v0
.LBB0_158:
	ds_read_b128 v[140:143], v148
	ds_read_b128 v[156:159], v148 offset:1024
	ds_read_b128 v[160:163], v148 offset:2048
	ds_read_b128 v[164:167], v148 offset:3072
	ds_read_b128 v[168:171], v149
	ds_read_b128 v[172:175], v149 offset:1024
	ds_read_b128 v[188:191], v149 offset:2048
	ds_read_b128 v[192:195], v149 offset:3072
	s_add_u32 s58, s28, 0xfffc0080
	s_addc_u32 s59, s29, -1
	s_cmp_eq_u32 s63, 12
	s_cselect_b32 s61, s5, s59
	s_cselect_b32 s60, s7, s58
	s_cselect_b32 s59, s8, s62
	s_cselect_b32 s58, s17, s21
	v_lshl_add_u64 v[144:145], s[28:29], 0, v[134:135]
	s_add_i32 m0, s70, 0xc000
	ds_read_b128 v[196:199], v150
	ds_read_b128 v[200:203], v150 offset:1024
	ds_read_b128 v[204:207], v150 offset:2048
	ds_read_b128 v[208:211], v150 offset:3072
	ds_read_b128 v[212:215], v150 offset:4096
	ds_read_b128 v[216:219], v150 offset:5120
	ds_read_b128 v[220:223], v150 offset:6144
	ds_read_b128 v[224:227], v150 offset:7168
	global_load_lds_dwordx4 v[144:145], off
	v_lshl_add_u64 v[144:145], s[28:29], 0, v[136:137]
	s_add_i32 m0, s70, 0xe000
	s_nop 0
	global_load_lds_dwordx4 v[144:145], off
	s_cmp_eq_u32 s96, 0
	s_cbranch_scc0 .Lp1_loose1
	s_waitcnt vmcnt(8)
	s_branch .Lp1_wdone1
; #define PG8_STAGE(bufoff, gbase, voff) do { _Pragma("unroll") for (int _i = 0; _i < 2; ++_i) \
;         __builtin_amdgcn_global_load_lds((const unsigned*)((const char*)(gbase) + (voff)[_i]), (PG8_LAS unsigned*)(lds + (bufoff) + ldsw + _i * 8192), 16, 0, 0); } while (0)
; #define PG8_LDA(dst, b, h) do { _Pragma("unroll") for (int m = 0; m < 4; ++m) _Pragma("unroll") for (int k = 0; k < 2; ++k) dst[m][k] = *(const PG8_LAS bf16x8*)(lds + PG8_SA(b, h) + aoff + m * 2048 + k * 1024); } while (0)
; #define PG8_MMA(ai, bj, At, Bt) do { __builtin_amdgcn_s_setprio(1); _Pragma("unroll") for (int m = 0; m < 4; ++m) _Pragma("unroll") for (int n = 0; n < 2; ++n) _Pragma("unroll") for (int k = 0; k < 2; ++k) \
;         acc[ai][bj][m][n] = __builtin_amdgcn_mfma_f32_16x16x32_bf16(Bt[n][k], At[m][k], acc[ai][bj][m][n], 0, 0, 0); __builtin_amdgcn_s_setprio(0); } while (0)
; #define PG8_WAIT_V(n) asm volatile("s_waitcnt vmcnt(" #n ")" ::: "memory")
; #define PG8_WAIT_L(n) asm volatile("s_waitcnt lgkmcnt(" #n ")" ::: "memory")
; #define PG8_BAR __builtin_amdgcn_s_barrier()
; #define PG8_SCHED __builtin_amdgcn_sched_barrier(0)
; template <class Epi, class Sched, bool ALIGN_EPI = false, bool SP2 = false>
; __device__ __forceinline__ void gemm_phase(PG8_LAS unsigned char* lds, const Gemm g, const Sched& S, const Epi& E) {
;     ...
;             PG8_WAIT_V(8); PG8_WAIT_L(0); PG8_BAR; PG8_MMA(0, 0, At, B0); PG8_MMA(0, 1, At, B1); PG8_BAR; PG8_SCHED;
;             PG8_LDA(At, 0, 1); PG8_STAGE(PG8_SB(0, 0), b2, voffB); PG8_STAGE(PG8_SB(0, 1), b2 + hstepB, voffB); PG8_STAGE(PG8_SA(0, 0), a2, voffA);
;             PG8_WAIT_V(8); PG8_WAIT_L(0); PG8_BAR; PG8_MMA(1, 0, At, B0); PG8_MMA(1, 1, At, B1); PG8_BAR; PG8_SCHED;
.Lp1_loose1:
	s_waitcnt vmcnt(24)
.Lp1_wdone1:
	s_waitcnt lgkmcnt(0)
	s_barrier
	s_setprio 1
	s_waitcnt lgkmcnt(0)
	v_mfma_f32_16x16x32_bf16 v[124:127], v[140:143], v[196:199], v[124:127]
	v_mfma_f32_16x16x32_bf16 v[120:123], v[160:163], v[196:199], v[120:123]
	v_mfma_f32_16x16x32_bf16 v[108:111], v[140:143], v[204:207], v[108:111]
	v_mfma_f32_16x16x32_bf16 v[104:107], v[160:163], v[204:207], v[104:107]
	v_mfma_f32_16x16x32_bf16 v[92:95], v[140:143], v[212:215], v[92:95]
	v_mfma_f32_16x16x32_bf16 v[88:91], v[160:163], v[212:215], v[88:91]
	v_mfma_f32_16x16x32_bf16 v[76:79], v[140:143], v[220:223], v[76:79]
	v_mfma_f32_16x16x32_bf16 v[72:75], v[160:163], v[220:223], v[72:75]
	v_mfma_f32_16x16x32_bf16 v[124:127], v[156:159], v[200:203], v[124:127]
	v_mfma_f32_16x16x32_bf16 v[120:123], v[164:167], v[200:203], v[120:123]
	v_mfma_f32_16x16x32_bf16 v[108:111], v[156:159], v[208:211], v[108:111]
	v_mfma_f32_16x16x32_bf16 v[104:107], v[164:167], v[208:211], v[104:107]
	v_mfma_f32_16x16x32_bf16 v[92:95], v[156:159], v[216:219], v[92:95]
	v_mfma_f32_16x16x32_bf16 v[88:91], v[164:167], v[216:219], v[88:91]
	v_mfma_f32_16x16x32_bf16 v[76:79], v[156:159], v[224:227], v[76:79]
	v_mfma_f32_16x16x32_bf16 v[72:75], v[164:167], v[224:227], v[72:75]
	s_setprio 0
	s_setprio 1
	v_mfma_f32_16x16x32_bf16 v[116:119], v[168:171], v[196:199], v[116:119]
	v_mfma_f32_16x16x32_bf16 v[112:115], v[188:191], v[196:199], v[112:115]
	v_mfma_f32_16x16x32_bf16 v[100:103], v[168:171], v[204:207], v[100:103]
	v_mfma_f32_16x16x32_bf16 v[96:99], v[188:191], v[204:207], v[96:99]
	v_mfma_f32_16x16x32_bf16 v[84:87], v[168:171], v[212:215], v[84:87]
	v_mfma_f32_16x16x32_bf16 v[80:83], v[188:191], v[212:215], v[80:83]
	v_mfma_f32_16x16x32_bf16 v[68:71], v[168:171], v[220:223], v[68:71]
	v_mfma_f32_16x16x32_bf16 v[64:67], v[188:191], v[220:223], v[64:67]
	v_mfma_f32_16x16x32_bf16 v[116:119], v[172:175], v[200:203], v[116:119]
	v_mfma_f32_16x16x32_bf16 v[112:115], v[192:195], v[200:203], v[112:115]
	v_mfma_f32_16x16x32_bf16 v[100:103], v[172:175], v[208:211], v[100:103]
	v_mfma_f32_16x16x32_bf16 v[96:99], v[192:195], v[208:211], v[96:99]
	v_mfma_f32_16x16x32_bf16 v[84:87], v[172:175], v[216:219], v[84:87]
	v_mfma_f32_16x16x32_bf16 v[80:83], v[192:195], v[216:219], v[80:83]
	v_mfma_f32_16x16x32_bf16 v[68:71], v[172:175], v[224:227], v[68:71]
	v_mfma_f32_16x16x32_bf16 v[64:67], v[192:195], v[224:227], v[64:67]
	s_setprio 0
	s_barrier
	s_add_i32 s64, s88, s69
	v_lshl_add_u64 v[144:145], s[58:59], 0, v[128:129]
	s_mov_b32 m0, s64
	ds_read_b128 v[196:199], v150 offset:16384
	ds_read_b128 v[200:203], v150 offset:17408
	ds_read_b128 v[204:207], v150 offset:18432
	ds_read_b128 v[208:211], v150 offset:19456
	ds_read_b128 v[212:215], v150 offset:20480
	ds_read_b128 v[216:219], v150 offset:21504
	ds_read_b128 v[220:223], v150 offset:22528
	ds_read_b128 v[224:227], v150 offset:23552
	global_load_lds_dwordx4 v[144:145], off
	s_add_i32 m0, s64, 0x2000
	s_add_u32 s64, s58, 0x10000
	v_lshl_add_u64 v[176:177], s[58:59], 0, v[130:131]
	s_addc_u32 s65, s59, 0
	s_add_i32 s66, s89, s69
	global_load_lds_dwordx4 v[176:177], off
	v_lshl_add_u64 v[228:229], s[64:65], 0, v[128:129]
	s_mov_b32 m0, s66
	v_lshl_add_u64 v[230:231], s[60:61], 0, v[154:155]
	global_load_lds_dwordx4 v[228:229], off
	v_lshl_add_u64 v[228:229], s[64:65], 0, v[130:131]
	s_add_i32 m0, s66, 0x2000
	s_nop 0
	global_load_lds_dwordx4 v[228:229], off
	v_lshl_add_u64 v[228:229], s[60:61], 0, v[152:153]
	s_mov_b32 m0, s70
	s_nop 0
	global_load_lds_dwordx4 v[228:229], off
	s_mov_b32 m0, s71
	s_nop 0
	global_load_lds_dwordx4 v[230:231], off
	s_cmp_eq_u32 s96, 0
	s_cbranch_scc0 .Lp1_loose2
	s_waitcnt vmcnt(8)
	s_branch .Lp1_wdone2

; #define PG8_STAGE(bufoff, gbase, voff) do { _Pragma("unroll") for (int _i = 0; _i < 2; ++_i) \
;         __builtin_amdgcn_global_load_lds((const unsigned*)((const char*)(gbase) + (voff)[_i]), (PG8_LAS unsigned*)(lds + (bufoff) + ldsw + _i * 8192), 16, 0, 0); } while (0)
; #define PG8_LDA(dst, b, h) do { _Pragma("unroll") for (int m = 0; m < 4; ++m) _Pragma("unroll") for (int k = 0; k < 2; ++k) dst[m][k] = *(const PG8_LAS bf16x8*)(lds + PG8_SA(b, h) + aoff + m * 2048 + k * 1024); } while (0)
; #define PG8_LDB(dst, b, h) do { _Pragma("unroll") for (int n = 0; n < 2; ++n) _Pragma("unroll") for (int k = 0; k < 2; ++k) dst[n][k] = *(const PG8_LAS bf16x8*)(lds + PG8_SB(b, h) + boff + n * 2048 + k * 1024); } while (0)
; #define PG8_MMA(ai, bj, At, Bt) do { __builtin_amdgcn_s_setprio(1); _Pragma("unroll") for (int m = 0; m < 4; ++m) _Pragma("unroll") for (int n = 0; n < 2; ++n) _Pragma("unroll") for (int k = 0; k < 2; ++k) \
;         acc[ai][bj][m][n] = __builtin_amdgcn_mfma_f32_16x16x32_bf16(Bt[n][k], At[m][k], acc[ai][bj][m][n], 0, 0, 0); __builtin_amdgcn_s_setprio(0); } while (0)
; #define PG8_WAIT_V(n) asm volatile("s_waitcnt vmcnt(" #n ")" ::: "memory")
; #define PG8_WAIT_L(n) asm volatile("s_waitcnt lgkmcnt(" #n ")" ::: "memory")
; #define PG8_BAR __builtin_amdgcn_s_barrier()
; #define PG8_SCHED __builtin_amdgcn_sched_barrier(0)
; template <class Epi, class Sched, bool ALIGN_EPI = false, bool SP2 = false>
; __device__ __forceinline__ void gemm_phase(PG8_LAS unsigned char* lds, const Gemm g, const Sched& S, const Epi& E) {
;     ...
;             PG8_WAIT_V(8); PG8_WAIT_L(0); PG8_BAR; PG8_MMA(1, 0, At, B0); PG8_MMA(1, 1, At, B1); PG8_BAR; PG8_SCHED;
;             PG8_LDB(B0, 1, 0); PG8_LDB(B1, 1, 1); PG8_SCHED; PG8_LDA(At, 1, 0); PG8_STAGE(PG8_SA(0, 1), a2 + hstep, voffA);
;             PG8_WAIT_V(8); PG8_WAIT_L(0); PG8_BAR; PG8_MMA(0, 0, At, B0); PG8_MMA(0, 1, At, B1); PG8_BAR; PG8_SCHED;
.Lp1_wdone2:
	s_waitcnt lgkmcnt(0)
	s_barrier
	s_setprio 1
	s_waitcnt lgkmcnt(0)
	v_mfma_f32_16x16x32_bf16 v[60:63], v[140:143], v[196:199], v[60:63]
	v_mfma_f32_16x16x32_bf16 v[56:59], v[160:163], v[196:199], v[56:59]
	v_mfma_f32_16x16x32_bf16 v[44:47], v[140:143], v[204:207], v[44:47]
	v_mfma_f32_16x16x32_bf16 v[40:43], v[160:163], v[204:207], v[40:43]
	v_mfma_f32_16x16x32_bf16 v[28:31], v[140:143], v[212:215], v[28:31]
	v_mfma_f32_16x16x32_bf16 v[24:27], v[160:163], v[212:215], v[24:27]
	v_mfma_f32_16x16x32_bf16 v[12:15], v[140:143], v[220:223], v[12:15]
	v_mfma_f32_16x16x32_bf16 v[8:11], v[160:163], v[220:223], v[8:11]
	v_mfma_f32_16x16x32_bf16 v[60:63], v[156:159], v[200:203], v[60:63]
	v_mfma_f32_16x16x32_bf16 v[56:59], v[164:167], v[200:203], v[56:59]
	v_mfma_f32_16x16x32_bf16 v[44:47], v[156:159], v[208:211], v[44:47]
	v_mfma_f32_16x16x32_bf16 v[40:43], v[164:167], v[208:211], v[40:43]
	v_mfma_f32_16x16x32_bf16 v[28:31], v[156:159], v[216:219], v[28:31]
	v_mfma_f32_16x16x32_bf16 v[24:27], v[164:167], v[216:219], v[24:27]
	v_mfma_f32_16x16x32_bf16 v[12:15], v[156:159], v[224:227], v[12:15]
	v_mfma_f32_16x16x32_bf16 v[8:11], v[164:167], v[224:227], v[8:11]
	s_setprio 0
	s_setprio 1
	v_mfma_f32_16x16x32_bf16 v[52:55], v[168:171], v[196:199], v[52:55]
	v_mfma_f32_16x16x32_bf16 v[48:51], v[188:191], v[196:199], v[48:51]
	v_mfma_f32_16x16x32_bf16 v[36:39], v[168:171], v[204:207], v[36:39]
	v_mfma_f32_16x16x32_bf16 v[32:35], v[188:191], v[204:207], v[32:35]
	v_mfma_f32_16x16x32_bf16 v[20:23], v[168:171], v[212:215], v[20:23]
	v_mfma_f32_16x16x32_bf16 v[16:19], v[188:191], v[212:215], v[16:19]
	v_mfma_f32_16x16x32_bf16 v[4:7], v[168:171], v[220:223], v[4:7]
	v_mfma_f32_16x16x32_bf16 v[0:3], v[188:191], v[220:223], v[0:3]
	v_mfma_f32_16x16x32_bf16 v[52:55], v[172:175], v[200:203], v[52:55]
	v_mfma_f32_16x16x32_bf16 v[48:51], v[192:195], v[200:203], v[48:51]
	v_mfma_f32_16x16x32_bf16 v[36:39], v[172:175], v[208:211], v[36:39]
	v_mfma_f32_16x16x32_bf16 v[32:35], v[192:195], v[208:211], v[32:35]
	v_mfma_f32_16x16x32_bf16 v[20:23], v[172:175], v[216:219], v[20:23]
	v_mfma_f32_16x16x32_bf16 v[16:19], v[192:195], v[216:219], v[16:19]
	v_mfma_f32_16x16x32_bf16 v[4:7], v[172:175], v[224:227], v[4:7]
	v_mfma_f32_16x16x32_bf16 v[0:3], v[192:195], v[224:227], v[0:3]
	s_setprio 0
	s_barrier
	s_add_i32 s64, 0, 0x18000
	v_add_u32_e32 v151, s64, v146
	s_add_i32 s65, 0, 0x1c000
	ds_read_b128 v[140:143], v151
	ds_read_b128 v[156:159], v151 offset:1024
	ds_read_b128 v[160:163], v151 offset:2048
	ds_read_b128 v[164:167], v151 offset:3072
	v_add_u32_e32 v151, s65, v146
	ds_read_b128 v[168:171], v151
	ds_read_b128 v[172:175], v151 offset:1024
	ds_read_b128 v[188:191], v151 offset:2048
	ds_read_b128 v[192:195], v151 offset:3072
	s_add_u32 s60, s60, 0x40000
	s_addc_u32 s61, s61, 0
	s_mov_b32 m0, s72
	v_lshl_add_u64 v[232:233], s[60:61], 0, v[152:153]
	ds_read_b128 v[196:199], v150 offset:32768
	ds_read_b128 v[200:203], v150 offset:33792
	ds_read_b128 v[204:207], v150 offset:34816
	ds_read_b128 v[208:211], v150 offset:35840
	ds_read_b128 v[212:215], v150 offset:36864
	ds_read_b128 v[216:219], v150 offset:37888
	ds_read_b128 v[220:223], v150 offset:38912
	ds_read_b128 v[224:227], v150 offset:39936
	global_load_lds_dwordx4 v[232:233], off
	v_lshl_add_u64 v[232:233], s[60:61], 0, v[154:155]
	s_mov_b32 m0, s73
	s_nop 0
	global_load_lds_dwordx4 v[232:233], off
	s_waitcnt vmcnt(8)
	s_waitcnt lgkmcnt(0)
	s_barrier
	s_setprio 1
	s_waitcnt lgkmcnt(0)
	v_mfma_f32_16x16x32_bf16 v[124:127], v[140:143], v[196:199], v[124:127]
	v_mfma_f32_16x16x32_bf16 v[120:123], v[160:163], v[196:199], v[120:123]
	v_mfma_f32_16x16x32_bf16 v[108:111], v[140:143], v[204:207], v[108:111]
	v_mfma_f32_16x16x32_bf16 v[104:107], v[160:163], v[204:207], v[104:107]
	v_mfma_f32_16x16x32_bf16 v[92:95], v[140:143], v[212:215], v[92:95]
	v_mfma_f32_16x16x32_bf16 v[88:91], v[160:163], v[212:215], v[88:91]
	v_mfma_f32_16x16x32_bf16 v[76:79], v[140:143], v[220:223], v[76:79]
	v_mfma_f32_16x16x32_bf16 v[72:75], v[160:163], v[220:223], v[72:75]
	v_mfma_f32_16x16x32_bf16 v[124:127], v[156:159], v[200:203], v[124:127]
	v_mfma_f32_16x16x32_bf16 v[120:123], v[164:167], v[200:203], v[120:123]
	v_mfma_f32_16x16x32_bf16 v[108:111], v[156:159], v[208:211], v[108:111]
	v_mfma_f32_16x16x32_bf16 v[104:107], v[164:167], v[208:211], v[104:107]
	v_mfma_f32_16x16x32_bf16 v[92:95], v[156:159], v[216:219], v[92:95]
	v_mfma_f32_16x16x32_bf16 v[88:91], v[164:167], v[216:219], v[88:91]
	v_mfma_f32_16x16x32_bf16 v[76:79], v[156:159], v[224:227], v[76:79]
	v_mfma_f32_16x16x32_bf16 v[72:75], v[164:167], v[224:227], v[72:75]
	s_setprio 0
	s_setprio 1
	v_mfma_f32_16x16x32_bf16 v[116:119], v[168:171], v[196:199], v[116:119]
	v_mfma_f32_16x16x32_bf16 v[112:115], v[188:191], v[196:199], v[112:115]
	v_mfma_f32_16x16x32_bf16 v[100:103], v[168:171], v[204:207], v[100:103]
	v_mfma_f32_16x16x32_bf16 v[96:99], v[188:191], v[204:207], v[96:99]
	v_mfma_f32_16x16x32_bf16 v[84:87], v[168:171], v[212:215], v[84:87]
	v_mfma_f32_16x16x32_bf16 v[80:83], v[188:191], v[212:215], v[80:83]
	v_mfma_f32_16x16x32_bf16 v[68:71], v[168:171], v[220:223], v[68:71]
	v_mfma_f32_16x16x32_bf16 v[64:67], v[188:191], v[220:223], v[64:67]
	v_mfma_f32_16x16x32_bf16 v[116:119], v[172:175], v[200:203], v[116:119]
	v_mfma_f32_16x16x32_bf16 v[112:115], v[192:195], v[200:203], v[112:115]
	v_mfma_f32_16x16x32_bf16 v[100:103], v[172:175], v[208:211], v[100:103]
	v_mfma_f32_16x16x32_bf16 v[96:99], v[192:195], v[208:211], v[96:99]
	v_mfma_f32_16x16x32_bf16 v[84:87], v[172:175], v[216:219], v[84:87]
	v_mfma_f32_16x16x32_bf16 v[80:83], v[192:195], v[216:219], v[80:83]
	v_mfma_f32_16x16x32_bf16 v[68:71], v[172:175], v[224:227], v[68:71]
	v_mfma_f32_16x16x32_bf16 v[64:67], v[192:195], v[224:227], v[64:67]
	s_setprio 0
	s_barrier
; #define PG8_STAGE(bufoff, gbase, voff) do { _Pragma("unroll") for (int _i = 0; _i < 2; ++_i) \
;         __builtin_amdgcn_global_load_lds((const unsigned*)((const char*)(gbase) + (voff)[_i]), (PG8_LAS unsigned*)(lds + (bufoff) + ldsw + _i * 8192), 16, 0, 0); } while (0)
; #define PG8_LDA(dst, b, h) do { _Pragma("unroll") for (int m = 0; m < 4; ++m) _Pragma("unroll") for (int k = 0; k < 2; ++k) dst[m][k] = *(const PG8_LAS bf16x8*)(lds + PG8_SA(b, h) + aoff + m * 2048 + k * 1024); } while (0)
; #define PG8_LDB(dst, b, h) do { _Pragma("unroll") for (int n = 0; n < 2; ++n) _Pragma("unroll") for (int k = 0; k < 2; ++k) dst[n][k] = *(const PG8_LAS bf16x8*)(lds + PG8_SB(b, h) + boff + n * 2048 + k * 1024); } while (0)
; template <class Epi, class Sched, bool ALIGN_EPI = false, bool SP2 = false>
; __device__ __forceinline__ void gemm_phase(PG8_LAS unsigned char* lds, const Gemm g, const Sched& S, const Epi& E) {
;     ...
;         for (int t = 0; t < nt; t += 2) {
;             const bool last = (t == nt - 2);
;             const char* a1 = cA + (size_t)(t + 1) * kstep;
;             const char* a2 = last ? nA : cA + (size_t)(t + 2) * kstep; const char* b2 = last ? nB : cB + (size_t)(t + 2) * kstep;
;             const char* a3 = a2 + kstep; const char* b3 = b2 + kstep;
;             if (last && has_next) S.a_ready(nxt);
;             if constexpr (SP2) {
;             PG8_LDB(B0, 0, 0); PG8_LDB(B1, 0, 1); PG8_SCHED; PG8_LDA(At, 0, 0); PG8_STAGE(PG8_SA(1, 1), a1 + hstep, voffA);
;             PG8_WAIT_V(8); PG8_WAIT_L(0); PG8_BAR; PG8_MMA(0, 0, At, B0); PG8_MMA(0, 1, At, B1); PG8_BAR; PG8_SCHED;
;             PG8_LDA(At, 0, 1); PG8_STAGE(PG8_SB(0, 0), b2, voffB); PG8_STAGE(PG8_SB(0, 1), b2 + hstepB, voffB); PG8_STAGE(PG8_SA(0, 0), a2, voffA);
;             PG8_WAIT_V(8); PG8_WAIT_L(0); PG8_BAR; PG8_MMA(1, 0, At, B0); PG8_MMA(1, 1, At, B1); PG8_BAR; PG8_SCHED;
;             PG8_LDB(B0, 1, 0); PG8_LDB(B1, 1, 1); PG8_SCHED; PG8_LDA(At, 1, 0); PG8_STAGE(PG8_SA(0, 1), a2 + hstep, voffA);
;             PG8_WAIT_V(8); PG8_WAIT_L(0); PG8_BAR; PG8_MMA(0, 0, At, B0); PG8_MMA(0, 1, At, B1); PG8_BAR; PG8_SCHED;
;             PG8_LDA(At, 1, 1); PG8_STAGE(PG8_SB(1, 0), b3, voffB); PG8_STAGE(PG8_SB(1, 1), b3 + hstepB, voffB); PG8_STAGE(PG8_SA(1, 0), a3, voffA);
;             PG8_WAIT_V(8); PG8_WAIT_L(0); PG8_BAR; PG8_MMA(1, 0, At, B0); PG8_MMA(1, 1, At, B1); PG8_BAR; PG8_SCHED;
	s_add_i32 s60, s64, s69
	v_lshl_add_u64 v[144:145], v[144:145], 0, s[12:13]
	s_mov_b32 m0, s60
	ds_read_b128 v[196:199], v150 offset:49152
	ds_read_b128 v[200:203], v150 offset:50176
	ds_read_b128 v[204:207], v150 offset:51200
	ds_read_b128 v[208:211], v150 offset:52224
	ds_read_b128 v[212:215], v150 offset:53248
	ds_read_b128 v[216:219], v150 offset:54272
	ds_read_b128 v[220:223], v150 offset:55296
	ds_read_b128 v[224:227], v150 offset:56320
	global_load_lds_dwordx4 v[144:145], off
	s_add_i32 m0, s60, 0x2000
	s_add_u32 s58, s58, 0x10080
	v_lshl_add_u64 v[144:145], v[176:177], 0, s[12:13]
	s_addc_u32 s59, s59, 0
	s_add_i32 s60, s65, s69
	global_load_lds_dwordx4 v[144:145], off
	v_lshl_add_u64 v[144:145], s[58:59], 0, v[128:129]
	s_mov_b32 m0, s60
	s_nop 0
	global_load_lds_dwordx4 v[144:145], off
	v_lshl_add_u64 v[144:145], s[58:59], 0, v[130:131]
	s_add_i32 m0, s60, 0x2000
	s_nop 0
	global_load_lds_dwordx4 v[144:145], off
	v_lshl_add_u64 v[144:145], v[228:229], 0, s[12:13]
	s_mov_b32 m0, s75
	s_nop 0
	global_load_lds_dwordx4 v[144:145], off
	v_lshl_add_u64 v[144:145], v[230:231], 0, s[12:13]
	s_mov_b32 m0, s76
	s_nop 0
	global_load_lds_dwordx4 v[144:145], off
	s_waitcnt vmcnt(8)
	s_waitcnt lgkmcnt(0)
	s_barrier
	s_setprio 1
	s_waitcnt lgkmcnt(0)
	v_mfma_f32_16x16x32_bf16 v[60:63], v[140:143], v[196:199], v[60:63]
	v_mfma_f32_16x16x32_bf16 v[56:59], v[160:163], v[196:199], v[56:59]
	v_mfma_f32_16x16x32_bf16 v[44:47], v[140:143], v[204:207], v[44:47]
	v_mfma_f32_16x16x32_bf16 v[40:43], v[160:163], v[204:207], v[40:43]
	v_mfma_f32_16x16x32_bf16 v[28:31], v[140:143], v[212:215], v[28:31]
	v_mfma_f32_16x16x32_bf16 v[24:27], v[160:163], v[212:215], v[24:27]
	v_mfma_f32_16x16x32_bf16 v[12:15], v[140:143], v[220:223], v[12:15]
	v_mfma_f32_16x16x32_bf16 v[8:11], v[160:163], v[220:223], v[8:11]
	v_mfma_f32_16x16x32_bf16 v[60:63], v[156:159], v[200:203], v[60:63]
	v_mfma_f32_16x16x32_bf16 v[56:59], v[164:167], v[200:203], v[56:59]
	v_mfma_f32_16x16x32_bf16 v[44:47], v[156:159], v[208:211], v[44:47]
	v_mfma_f32_16x16x32_bf16 v[40:43], v[164:167], v[208:211], v[40:43]
	v_mfma_f32_16x16x32_bf16 v[28:31], v[156:159], v[216:219], v[28:31]
	v_mfma_f32_16x16x32_bf16 v[24:27], v[164:167], v[216:219], v[24:27]
	v_mfma_f32_16x16x32_bf16 v[12:15], v[156:159], v[224:227], v[12:15]
	v_mfma_f32_16x16x32_bf16 v[8:11], v[164:167], v[224:227], v[8:11]
	s_setprio 0
	s_setprio 1
	v_mfma_f32_16x16x32_bf16 v[52:55], v[168:171], v[196:199], v[52:55]
	v_mfma_f32_16x16x32_bf16 v[48:51], v[188:191], v[196:199], v[48:51]
	v_mfma_f32_16x16x32_bf16 v[36:39], v[168:171], v[204:207], v[36:39]
	v_mfma_f32_16x16x32_bf16 v[32:35], v[188:191], v[204:207], v[32:35]
	v_mfma_f32_16x16x32_bf16 v[20:23], v[168:171], v[212:215], v[20:23]
	v_mfma_f32_16x16x32_bf16 v[16:19], v[188:191], v[212:215], v[16:19]
	v_mfma_f32_16x16x32_bf16 v[4:7], v[168:171], v[220:223], v[4:7]
	v_mfma_f32_16x16x32_bf16 v[0:3], v[188:191], v[220:223], v[0:3]
	v_mfma_f32_16x16x32_bf16 v[52:55], v[172:175], v[200:203], v[52:55]
	v_mfma_f32_16x16x32_bf16 v[48:51], v[192:195], v[200:203], v[48:51]
	v_mfma_f32_16x16x32_bf16 v[36:39], v[172:175], v[208:211], v[36:39]
	v_mfma_f32_16x16x32_bf16 v[32:35], v[192:195], v[208:211], v[32:35]
	v_mfma_f32_16x16x32_bf16 v[20:23], v[172:175], v[216:219], v[20:23]
	v_mfma_f32_16x16x32_bf16 v[16:19], v[192:195], v[216:219], v[16:19]
	v_mfma_f32_16x16x32_bf16 v[4:7], v[172:175], v[224:227], v[4:7]
	v_mfma_f32_16x16x32_bf16 v[0:3], v[192:195], v[224:227], v[0:3]
	s_setprio 0
	s_barrier
	s_add_i32 s63, s63, 2
	s_mov_b32 s96, 0
	s_add_u32 s28, s28, 0x100
	s_addc_u32 s29, s29, 0
	s_add_u32 s21, s21, 0x100
	s_addc_u32 s62, s62, 0
	s_cmp_gt_u32 s63, 13
	s_cbranch_scc0 .LBB0_158
	s_and_b64 vcc, exec, s[14:15]
	s_cbranch_vccz .LBB0_161
	s_barrier

;     __host__ __device__ bool next(int i, Unit& u) const {
;         const int per = (nwg + G - 1) / G; if (i >= per * rep) return false; const long L = (long)(i % per) * G + c; if (L >= nwg) return false;
;         int wgid = (int)L; { const int q = nwg / NXCD, r = nwg % NXCD, xcd = wgid % NXCD, off = wgid / NXCD; wgid = (xcd < r ? xcd * (q + 1) : r * (q + 1) + (xcd - r) * q) + off; }
;         const int nig = WGM * nN, gid = wgid / nig, fm = gid * WGM, gsz = (nM - fm) < WGM ? (nM - fm) : WGM;
;         u.pm = fm + ((wgid % nig) % gsz); u.pn = (wgid % nig) / gsz; return true;
; template <class Epi, class Sched, bool ALIGN_EPI = false, bool SP2 = false>
; __device__ __forceinline__ void gemm_phase(PG8_LAS unsigned char* lds, const Gemm g, const Sched& S, const Epi& E) {
;     ...
;     if (!S.next(0, cur)) return;
.LBB0_460:
	s_or_b64 exec, exec, s[0:1]
	s_add_i32 s0, s54, 0x3ff
	s_sub_i32 s3, 0xfffffc01, s54
	s_ashr_i32 s1, s0, 31
	s_max_i32 s0, s0, s3
	s_mul_hi_u32 s3, s0, s84
	s_mul_i32 s4, s3, s83
	s_sub_i32 s0, s0, s4
	s_xor_b32 s1, s1, s82
	s_add_i32 s4, s3, 1
	s_sub_i32 s5, s0, s83
	s_cmp_ge_u32 s0, s83
	s_cselect_b32 s3, s4, s3
	s_cselect_b32 s0, s5, s0
	s_add_i32 s4, s3, 1
	s_cmp_ge_u32 s0, s83
	s_cselect_b32 s0, s4, s3
	s_xor_b32 s0, s0, s1
	s_sub_i32 s3, s0, s1
	s_cmp_lt_i32 s3, 1
	s_cselect_b64 s[0:1], -1, 0
	s_cmpk_gt_i32 s2, 0x3ff
	s_cselect_b64 s[4:5], -1, 0
	s_or_b64 s[0:1], s[4:5], s[0:1]
	v_readfirstlane_b32 s7, v178
	s_and_b64 vcc, exec, s[0:1]
	s_waitcnt lgkmcnt(0)
	s_barrier
	s_cbranch_vccnz .LBB0_485
	s_mov_b32 s97, 0
	s_ashr_i32 s33, s2, 31
	s_lshr_b32 s0, s33, 29
	s_add_i32 s6, s2, s0
	s_and_b32 s0, s6, -8
	s_sub_i32 s4, s2, s0
	s_cmp_gt_i32 s4, -1
	s_cbranch_scc0 .LBB0_463
	s_lshl_b32 s5, s4, 7
	s_ashr_i32 s0, s6, 3
	s_cbranch_execz .LBB0_464
	s_branch .LBB0_465

; #define PG8_STAGE(bufoff, gbase, voff) do { _Pragma("unroll") for (int _i = 0; _i < 2; ++_i) \
;         __builtin_amdgcn_global_load_lds((const unsigned*)((const char*)(gbase) + (voff)[_i]), (PG8_LAS unsigned*)(lds + (bufoff) + ldsw + _i * 8192), 16, 0, 0); } while (0)
; #define PG8_LDA(dst, b, h) do { _Pragma("unroll") for (int m = 0; m < 4; ++m) _Pragma("unroll") for (int k = 0; k < 2; ++k) dst[m][k] = *(const PG8_LAS bf16x8*)(lds + PG8_SA(b, h) + aoff + m * 2048 + k * 1024); } while (0)
; #define PG8_LDB(dst, b, h) do { _Pragma("unroll") for (int n = 0; n < 2; ++n) _Pragma("unroll") for (int k = 0; k < 2; ++k) dst[n][k] = *(const PG8_LAS bf16x8*)(lds + PG8_SB(b, h) + boff + n * 2048 + k * 1024); } while (0)
; #define PG8_WAIT_V(n) asm volatile("s_waitcnt vmcnt(" #n ")" ::: "memory")
; #define PG8_WAIT_L(n) asm volatile("s_waitcnt lgkmcnt(" #n ")" ::: "memory")
; #define PG8_BAR __builtin_amdgcn_s_barrier()
; template <class Epi, class Sched, bool ALIGN_EPI = false, bool SP2 = false>
; __device__ __forceinline__ void gemm_phase(PG8_LAS unsigned char* lds, const Gemm g, const Sched& S, const Epi& E) {
;     ...
;         const bool has_next = S.next(ui + 1, nxt);
;         const char* nA = has_next ? (const char*)g.A + (size_t)nxt.pm * tstep : cA; const char* nB = has_next ? (const char*)g.Bt + (size_t)nxt.pn * tstep : cB;
;         for (int t = 0; t < nt; t += 2) {
;             const bool last = (t == nt - 2);
;             const char* a1 = cA + (size_t)(t + 1) * kstep;
;             const char* a2 = last ? nA : cA + (size_t)(t + 2) * kstep; const char* b2 = last ? nB : cB + (size_t)(t + 2) * kstep;
;             const char* a3 = a2 + kstep; const char* b3 = b2 + kstep;
;             if (last && has_next) S.a_ready(nxt);
;             if constexpr (SP2) {
;             PG8_LDB(B0, 0, 0); PG8_LDB(B1, 0, 1); PG8_SCHED; PG8_LDA(At, 0, 0); PG8_STAGE(PG8_SA(1, 1), a1 + hstep, voffA);
;             PG8_WAIT_V(8); PG8_WAIT_L(0); PG8_BAR; PG8_MMA(0, 0, At, B0); PG8_MMA(0, 1, At, B1); PG8_BAR; PG8_SCHED;
;     ...
; #pragma unroll
;         for (int a = 0; a < 2; ++a)
; #pragma unroll
;             for (int b = 0; b < 2; ++b)
; #pragma unroll
;                 for (int m = 0; m < 4; ++m)
; #pragma unroll
;                     for (int n = 0; n < 2; ++n) acc[a][b][m][n] = (f32x4){0.f, 0.f, 0.f, 0.f};
;         cur = nxt; cA = nA; cB = nB; ++ui;
.LBB0_477:
	s_ashr_i32 s19, s18, 31
	s_lshl_b64 s[22:23], s[18:19], 19
	s_add_u32 s22, s38, s22
	s_addc_u32 s23, s39, s23
	s_and_b64 s[24:25], s[20:21], exec
	s_cselect_b32 s19, s23, s29
	s_cselect_b32 s56, s22, s28
	s_ashr_i32 s17, s16, 31
	s_lshl_b64 s[24:25], s[16:17], 19
	s_add_u32 s24, s30, s24
	s_addc_u32 s25, s31, s25
	s_and_b64 s[40:41], s[20:21], exec
	s_cselect_b32 s17, s25, s35
	s_cselect_b32 s57, s24, s34
	s_add_u32 s28, s28, 0x40080
	s_addc_u32 s29, s29, 0
	s_add_u32 s58, s34, 0x100
	v_mov_b32_e32 v0, 0
	s_addc_u32 s59, s35, 0
	s_mov_b32 s60, -2
	s_mov_b32 s99, s97
	s_mov_b32 s97, 1
	v_mov_b32_e32 v1, v0
	v_mov_b32_e32 v2, v0
	v_mov_b32_e32 v3, v0
	v_mov_b32_e32 v4, v0
	v_mov_b32_e32 v5, v0
	v_mov_b32_e32 v6, v0
	v_mov_b32_e32 v7, v0
	v_mov_b32_e32 v8, v0
	v_mov_b32_e32 v9, v0
	v_mov_b32_e32 v10, v0
	v_mov_b32_e32 v11, v0
	v_mov_b32_e32 v20, v0
	v_mov_b32_e32 v21, v0
	v_mov_b32_e32 v22, v0
	v_mov_b32_e32 v23, v0
	v_mov_b32_e32 v24, v0
	v_mov_b32_e32 v25, v0
	v_mov_b32_e32 v26, v0
	v_mov_b32_e32 v27, v0
	v_mov_b32_e32 v36, v0
	v_mov_b32_e32 v37, v0
	v_mov_b32_e32 v38, v0
	v_mov_b32_e32 v39, v0
	v_mov_b32_e32 v40, v0
	v_mov_b32_e32 v41, v0
	v_mov_b32_e32 v42, v0
	v_mov_b32_e32 v43, v0
	v_mov_b32_e32 v52, v0
	v_mov_b32_e32 v53, v0
	v_mov_b32_e32 v54, v0
	v_mov_b32_e32 v55, v0
	v_mov_b32_e32 v12, v0
	v_mov_b32_e32 v13, v0
	v_mov_b32_e32 v14, v0
	v_mov_b32_e32 v15, v0
	v_mov_b32_e32 v16, v0
	v_mov_b32_e32 v17, v0
	v_mov_b32_e32 v18, v0
	v_mov_b32_e32 v19, v0
	v_mov_b32_e32 v28, v0
	v_mov_b32_e32 v29, v0
	v_mov_b32_e32 v30, v0
	v_mov_b32_e32 v31, v0
	v_mov_b32_e32 v32, v0
	v_mov_b32_e32 v33, v0
	v_mov_b32_e32 v34, v0
	v_mov_b32_e32 v35, v0
	v_mov_b32_e32 v44, v0
	v_mov_b32_e32 v45, v0
	v_mov_b32_e32 v46, v0
	v_mov_b32_e32 v47, v0
	v_mov_b32_e32 v48, v0
	v_mov_b32_e32 v49, v0
	v_mov_b32_e32 v50, v0
	v_mov_b32_e32 v51, v0
	v_mov_b32_e32 v56, v0
	v_mov_b32_e32 v57, v0
	v_mov_b32_e32 v58, v0
	v_mov_b32_e32 v59, v0
	v_mov_b32_e32 v60, v0
	v_mov_b32_e32 v61, v0
	v_mov_b32_e32 v62, v0
	v_mov_b32_e32 v63, v0
	v_mov_b32_e32 v64, v0
	v_mov_b32_e32 v65, v0
	v_mov_b32_e32 v66, v0
	v_mov_b32_e32 v67, v0
	v_mov_b32_e32 v68, v0
	v_mov_b32_e32 v69, v0
	v_mov_b32_e32 v70, v0
	v_mov_b32_e32 v71, v0
	v_mov_b32_e32 v72, v0
	v_mov_b32_e32 v73, v0
	v_mov_b32_e32 v74, v0
	v_mov_b32_e32 v75, v0
	v_mov_b32_e32 v84, v0
	v_mov_b32_e32 v85, v0
	v_mov_b32_e32 v86, v0
	v_mov_b32_e32 v87, v0
	v_mov_b32_e32 v88, v0
	v_mov_b32_e32 v89, v0
	v_mov_b32_e32 v90, v0
	v_mov_b32_e32 v91, v0
	v_mov_b32_e32 v100, v0
	v_mov_b32_e32 v101, v0
	v_mov_b32_e32 v102, v0
	v_mov_b32_e32 v103, v0
	v_mov_b32_e32 v104, v0
	v_mov_b32_e32 v105, v0
	v_mov_b32_e32 v106, v0
	v_mov_b32_e32 v107, v0
	v_mov_b32_e32 v116, v0
	v_mov_b32_e32 v117, v0
	v_mov_b32_e32 v118, v0
	v_mov_b32_e32 v119, v0
	v_mov_b32_e32 v76, v0
	v_mov_b32_e32 v77, v0
	v_mov_b32_e32 v78, v0
	v_mov_b32_e32 v79, v0
	v_mov_b32_e32 v80, v0
	v_mov_b32_e32 v81, v0
	v_mov_b32_e32 v82, v0
	v_mov_b32_e32 v83, v0
	v_mov_b32_e32 v92, v0
	v_mov_b32_e32 v93, v0
	v_mov_b32_e32 v94, v0
	v_mov_b32_e32 v95, v0
	v_mov_b32_e32 v96, v0
	v_mov_b32_e32 v97, v0
	v_mov_b32_e32 v98, v0
	v_mov_b32_e32 v99, v0
	v_mov_b32_e32 v108, v0
	v_mov_b32_e32 v109, v0
	v_mov_b32_e32 v110, v0
	v_mov_b32_e32 v111, v0
	v_mov_b32_e32 v112, v0
	v_mov_b32_e32 v113, v0
	v_mov_b32_e32 v114, v0
	v_mov_b32_e32 v115, v0
	v_mov_b32_e32 v120, v0
	v_mov_b32_e32 v121, v0
	v_mov_b32_e32 v122, v0
	v_mov_b32_e32 v123, v0
	v_mov_b32_e32 v124, v0
	v_mov_b32_e32 v125, v0
	v_mov_b32_e32 v126, v0
	v_mov_b32_e32 v127, v0
.LBB0_478:
	ds_read_b128 v[142:145], v139
	ds_read_b128 v[146:149], v139 offset:1024
	ds_read_b128 v[156:159], v139 offset:2048
	ds_read_b128 v[160:163], v139 offset:3072
	ds_read_b128 v[164:167], v140
	ds_read_b128 v[168:171], v140 offset:1024
	ds_read_b128 v[172:175], v140 offset:2048
	ds_read_b128 v[176:179], v140 offset:3072
	s_add_u32 s34, s28, 0xfffc0080
	s_addc_u32 s35, s29, -1
	s_cmp_eq_u32 s60, 12
	s_cselect_b32 s41, s19, s35
	s_cselect_b32 s40, s56, s34
	s_cselect_b32 s35, s17, s59
	s_cselect_b32 s34, s57, s58
	v_lshl_add_u64 v[134:135], s[28:29], 0, v[128:129]
	s_add_i32 m0, s27, 0xc000
	ds_read_b128 v[180:183], v141
	ds_read_b128 v[184:187], v141 offset:1024
	ds_read_b128 v[188:191], v141 offset:2048
	ds_read_b128 v[192:195], v141 offset:3072
	ds_read_b128 v[196:199], v141 offset:4096
	ds_read_b128 v[200:203], v141 offset:5120
	ds_read_b128 v[204:207], v141 offset:6144
	ds_read_b128 v[208:211], v141 offset:7168
	global_load_lds_dwordx4 v[134:135], off
	v_lshl_add_u64 v[134:135], s[28:29], 0, v[130:131]
	s_add_i32 m0, s27, 0xe000
	s_nop 0
	global_load_lds_dwordx4 v[134:135], off
	s_cmp_eq_u32 s99, 0
	s_cbranch_scc0 .Lp4_wdone1
	s_waitcnt vmcnt(8)
; #define PG8_STAGE(bufoff, gbase, voff) do { _Pragma("unroll") for (int _i = 0; _i < 2; ++_i) \
;         __builtin_amdgcn_global_load_lds((const unsigned*)((const char*)(gbase) + (voff)[_i]), (PG8_LAS unsigned*)(lds + (bufoff) + ldsw + _i * 8192), 16, 0, 0); } while (0)
; #define PG8_LDA(dst, b, h) do { _Pragma("unroll") for (int m = 0; m < 4; ++m) _Pragma("unroll") for (int k = 0; k < 2; ++k) dst[m][k] = *(const PG8_LAS bf16x8*)(lds + PG8_SA(b, h) + aoff + m * 2048 + k * 1024); } while (0)
; #define PG8_MMA(ai, bj, At, Bt) do { __builtin_amdgcn_s_setprio(1); _Pragma("unroll") for (int m = 0; m < 4; ++m) _Pragma("unroll") for (int n = 0; n < 2; ++n) _Pragma("unroll") for (int k = 0; k < 2; ++k) \
;         acc[ai][bj][m][n] = __builtin_amdgcn_mfma_f32_16x16x32_bf16(Bt[n][k], At[m][k], acc[ai][bj][m][n], 0, 0, 0); __builtin_amdgcn_s_setprio(0); } while (0)
; #define PG8_WAIT_V(n) asm volatile("s_waitcnt vmcnt(" #n ")" ::: "memory")
; #define PG8_WAIT_L(n) asm volatile("s_waitcnt lgkmcnt(" #n ")" ::: "memory")
; #define PG8_BAR __builtin_amdgcn_s_barrier()
; #define PG8_SCHED __builtin_amdgcn_sched_barrier(0)
; template <class Epi, class Sched, bool ALIGN_EPI = false, bool SP2 = false>
; __device__ __forceinline__ void gemm_phase(PG8_LAS unsigned char* lds, const Gemm g, const Sched& S, const Epi& E) {
;     ...
;             PG8_WAIT_V(8); PG8_WAIT_L(0); PG8_BAR; PG8_MMA(0, 0, At, B0); PG8_MMA(0, 1, At, B1); PG8_BAR; PG8_SCHED;
;             PG8_LDA(At, 0, 1); PG8_STAGE(PG8_SB(0, 0), b2, voffB); PG8_STAGE(PG8_SB(0, 1), b2 + hstepB, voffB); PG8_STAGE(PG8_SA(0, 0), a2, voffA);
;             PG8_WAIT_V(8); PG8_WAIT_L(0); PG8_BAR; PG8_MMA(1, 0, At, B0); PG8_MMA(1, 1, At, B1); PG8_BAR; PG8_SCHED;
.Lp4_wdone1:
	s_waitcnt lgkmcnt(0)
	s_barrier
	s_setprio 1
	s_waitcnt lgkmcnt(0)
	v_mfma_f32_16x16x32_bf16 v[124:127], v[142:145], v[180:183], v[124:127]
	v_mfma_f32_16x16x32_bf16 v[120:123], v[156:159], v[180:183], v[120:123]
	v_mfma_f32_16x16x32_bf16 v[112:115], v[142:145], v[188:191], v[112:115]
	v_mfma_f32_16x16x32_bf16 v[108:111], v[156:159], v[188:191], v[108:111]
	v_mfma_f32_16x16x32_bf16 v[96:99], v[142:145], v[196:199], v[96:99]
	v_mfma_f32_16x16x32_bf16 v[92:95], v[156:159], v[196:199], v[92:95]
	v_mfma_f32_16x16x32_bf16 v[80:83], v[142:145], v[204:207], v[80:83]
	v_mfma_f32_16x16x32_bf16 v[76:79], v[156:159], v[204:207], v[76:79]
	v_mfma_f32_16x16x32_bf16 v[124:127], v[146:149], v[184:187], v[124:127]
	v_mfma_f32_16x16x32_bf16 v[120:123], v[160:163], v[184:187], v[120:123]
	v_mfma_f32_16x16x32_bf16 v[112:115], v[146:149], v[192:195], v[112:115]
	v_mfma_f32_16x16x32_bf16 v[108:111], v[160:163], v[192:195], v[108:111]
	v_mfma_f32_16x16x32_bf16 v[96:99], v[146:149], v[200:203], v[96:99]
	v_mfma_f32_16x16x32_bf16 v[92:95], v[160:163], v[200:203], v[92:95]
	v_mfma_f32_16x16x32_bf16 v[80:83], v[146:149], v[208:211], v[80:83]
	v_mfma_f32_16x16x32_bf16 v[76:79], v[160:163], v[208:211], v[76:79]
	s_setprio 0
	s_setprio 1
	v_mfma_f32_16x16x32_bf16 v[116:119], v[164:167], v[180:183], v[116:119]
	v_mfma_f32_16x16x32_bf16 v[104:107], v[172:175], v[180:183], v[104:107]
	v_mfma_f32_16x16x32_bf16 v[100:103], v[164:167], v[188:191], v[100:103]
	v_mfma_f32_16x16x32_bf16 v[88:91], v[172:175], v[188:191], v[88:91]
	v_mfma_f32_16x16x32_bf16 v[84:87], v[164:167], v[196:199], v[84:87]
	v_mfma_f32_16x16x32_bf16 v[72:75], v[172:175], v[196:199], v[72:75]
	v_mfma_f32_16x16x32_bf16 v[68:71], v[164:167], v[204:207], v[68:71]
	v_mfma_f32_16x16x32_bf16 v[64:67], v[172:175], v[204:207], v[64:67]
	v_mfma_f32_16x16x32_bf16 v[116:119], v[168:171], v[184:187], v[116:119]
	v_mfma_f32_16x16x32_bf16 v[104:107], v[176:179], v[184:187], v[104:107]
	v_mfma_f32_16x16x32_bf16 v[100:103], v[168:171], v[192:195], v[100:103]
	v_mfma_f32_16x16x32_bf16 v[88:91], v[176:179], v[192:195], v[88:91]
	v_mfma_f32_16x16x32_bf16 v[84:87], v[168:171], v[200:203], v[84:87]
	v_mfma_f32_16x16x32_bf16 v[72:75], v[176:179], v[200:203], v[72:75]
	v_mfma_f32_16x16x32_bf16 v[68:71], v[168:171], v[208:211], v[68:71]
	v_mfma_f32_16x16x32_bf16 v[64:67], v[176:179], v[208:211], v[64:67]
	s_setprio 0
	s_barrier
	s_add_i32 s61, s52, s42
	v_lshl_add_u64 v[134:135], s[34:35], 0, v[152:153]
	s_mov_b32 m0, s61
	ds_read_b128 v[180:183], v141 offset:16384
	ds_read_b128 v[184:187], v141 offset:17408
	ds_read_b128 v[188:191], v141 offset:18432
	ds_read_b128 v[192:195], v141 offset:19456
	ds_read_b128 v[196:199], v141 offset:20480
	ds_read_b128 v[200:203], v141 offset:21504
	ds_read_b128 v[204:207], v141 offset:22528
	ds_read_b128 v[208:211], v141 offset:23552
	global_load_lds_dwordx4 v[134:135], off
	s_add_i32 m0, s61, 0x2000
	s_add_u32 s62, s34, 0x40000
	v_lshl_add_u64 v[150:151], s[34:35], 0, v[154:155]
	s_addc_u32 s63, s35, 0
	s_add_i32 s61, s53, s42
	global_load_lds_dwordx4 v[150:151], off
	v_lshl_add_u64 v[212:213], s[62:63], 0, v[152:153]
	s_mov_b32 m0, s61
	v_lshl_add_u64 v[214:215], s[40:41], 0, v[154:155]
	global_load_lds_dwordx4 v[212:213], off
	v_lshl_add_u64 v[212:213], s[62:63], 0, v[154:155]
	s_add_i32 m0, s61, 0x2000
	s_nop 0
	global_load_lds_dwordx4 v[212:213], off
	v_lshl_add_u64 v[212:213], s[40:41], 0, v[152:153]
	s_mov_b32 m0, s27
	s_nop 0
	global_load_lds_dwordx4 v[212:213], off
	s_mov_b32 m0, s43
	s_nop 0
	global_load_lds_dwordx4 v[214:215], off
	s_cmp_eq_u32 s99, 0
	s_cbranch_scc0 .Lp4_wdone2
	s_waitcnt vmcnt(8)
.Lp4_wdone2:
	s_waitcnt lgkmcnt(0)
	s_barrier
	s_setprio 1
	s_waitcnt lgkmcnt(0)
	v_mfma_f32_16x16x32_bf16 v[60:63], v[142:145], v[180:183], v[60:63]
	v_mfma_f32_16x16x32_bf16 v[56:59], v[156:159], v[180:183], v[56:59]
	v_mfma_f32_16x16x32_bf16 v[48:51], v[142:145], v[188:191], v[48:51]
	v_mfma_f32_16x16x32_bf16 v[44:47], v[156:159], v[188:191], v[44:47]
	v_mfma_f32_16x16x32_bf16 v[32:35], v[142:145], v[196:199], v[32:35]
	v_mfma_f32_16x16x32_bf16 v[28:31], v[156:159], v[196:199], v[28:31]
	v_mfma_f32_16x16x32_bf16 v[16:19], v[142:145], v[204:207], v[16:19]
	v_mfma_f32_16x16x32_bf16 v[12:15], v[156:159], v[204:207], v[12:15]
	v_mfma_f32_16x16x32_bf16 v[60:63], v[146:149], v[184:187], v[60:63]
	v_mfma_f32_16x16x32_bf16 v[56:59], v[160:163], v[184:187], v[56:59]
	v_mfma_f32_16x16x32_bf16 v[48:51], v[146:149], v[192:195], v[48:51]
	v_mfma_f32_16x16x32_bf16 v[44:47], v[160:163], v[192:195], v[44:47]
	v_mfma_f32_16x16x32_bf16 v[32:35], v[146:149], v[200:203], v[32:35]
	v_mfma_f32_16x16x32_bf16 v[28:31], v[160:163], v[200:203], v[28:31]
	v_mfma_f32_16x16x32_bf16 v[16:19], v[146:149], v[208:211], v[16:19]
	v_mfma_f32_16x16x32_bf16 v[12:15], v[160:163], v[208:211], v[12:15]
	s_setprio 0
	s_setprio 1
	v_mfma_f32_16x16x32_bf16 v[52:55], v[164:167], v[180:183], v[52:55]
	v_mfma_f32_16x16x32_bf16 v[40:43], v[172:175], v[180:183], v[40:43]
	v_mfma_f32_16x16x32_bf16 v[36:39], v[164:167], v[188:191], v[36:39]
	v_mfma_f32_16x16x32_bf16 v[24:27], v[172:175], v[188:191], v[24:27]
	v_mfma_f32_16x16x32_bf16 v[20:23], v[164:167], v[196:199], v[20:23]
	v_mfma_f32_16x16x32_bf16 v[8:11], v[172:175], v[196:199], v[8:11]
	v_mfma_f32_16x16x32_bf16 v[4:7], v[164:167], v[204:207], v[4:7]
	v_mfma_f32_16x16x32_bf16 v[0:3], v[172:175], v[204:207], v[0:3]
	v_mfma_f32_16x16x32_bf16 v[52:55], v[168:171], v[184:187], v[52:55]
	v_mfma_f32_16x16x32_bf16 v[40:43], v[176:179], v[184:187], v[40:43]
	v_mfma_f32_16x16x32_bf16 v[36:39], v[168:171], v[192:195], v[36:39]
	v_mfma_f32_16x16x32_bf16 v[24:27], v[176:179], v[192:195], v[24:27]
	v_mfma_f32_16x16x32_bf16 v[20:23], v[168:171], v[200:203], v[20:23]
	v_mfma_f32_16x16x32_bf16 v[8:11], v[176:179], v[200:203], v[8:11]
	v_mfma_f32_16x16x32_bf16 v[4:7], v[168:171], v[208:211], v[4:7]
	v_mfma_f32_16x16x32_bf16 v[0:3], v[176:179], v[208:211], v[0:3]
	s_setprio 0
	s_barrier
; #define PG8_STAGE(bufoff, gbase, voff) do { _Pragma("unroll") for (int _i = 0; _i < 2; ++_i) \
;         __builtin_amdgcn_global_load_lds((const unsigned*)((const char*)(gbase) + (voff)[_i]), (PG8_LAS unsigned*)(lds + (bufoff) + ldsw + _i * 8192), 16, 0, 0); } while (0)
; #define PG8_LDA(dst, b, h) do { _Pragma("unroll") for (int m = 0; m < 4; ++m) _Pragma("unroll") for (int k = 0; k < 2; ++k) dst[m][k] = *(const PG8_LAS bf16x8*)(lds + PG8_SA(b, h) + aoff + m * 2048 + k * 1024); } while (0)
; #define PG8_LDB(dst, b, h) do { _Pragma("unroll") for (int n = 0; n < 2; ++n) _Pragma("unroll") for (int k = 0; k < 2; ++k) dst[n][k] = *(const PG8_LAS bf16x8*)(lds + PG8_SB(b, h) + boff + n * 2048 + k * 1024); } while (0)
; #define PG8_MMA(ai, bj, At, Bt) do { __builtin_amdgcn_s_setprio(1); _Pragma("unroll") for (int m = 0; m < 4; ++m) _Pragma("unroll") for (int n = 0; n < 2; ++n) _Pragma("unroll") for (int k = 0; k < 2; ++k) \
;         acc[ai][bj][m][n] = __builtin_amdgcn_mfma_f32_16x16x32_bf16(Bt[n][k], At[m][k], acc[ai][bj][m][n], 0, 0, 0); __builtin_amdgcn_s_setprio(0); } while (0)
; #define PG8_WAIT_V(n) asm volatile("s_waitcnt vmcnt(" #n ")" ::: "memory")
; #define PG8_WAIT_L(n) asm volatile("s_waitcnt lgkmcnt(" #n ")" ::: "memory")
; #define PG8_BAR __builtin_amdgcn_s_barrier()
; #define PG8_SCHED __builtin_amdgcn_sched_barrier(0)
; template <class Epi, class Sched, bool ALIGN_EPI = false, bool SP2 = false>
; __device__ __forceinline__ void gemm_phase(PG8_LAS unsigned char* lds, const Gemm g, const Sched& S, const Epi& E) {
;     ...
;             PG8_LDB(B0, 1, 0); PG8_LDB(B1, 1, 1); PG8_SCHED; PG8_LDA(At, 1, 0); PG8_STAGE(PG8_SA(0, 1), a2 + hstep, voffA);
;             PG8_WAIT_V(8); PG8_WAIT_L(0); PG8_BAR; PG8_MMA(0, 0, At, B0); PG8_MMA(0, 1, At, B1); PG8_BAR; PG8_SCHED;
	s_add_i32 s61, 0, 0x18000
	s_add_i32 s62, 0, 0x1c000
	v_add_u32_e32 v160, s61, v137
	v_add_u32_e32 v176, s62, v137
	ds_read_b128 v[142:145], v160
	ds_read_b128 v[146:149], v160 offset:1024
	ds_read_b128 v[156:159], v160 offset:2048
	ds_read_b128 v[160:163], v160 offset:3072
	ds_read_b128 v[164:167], v176
	ds_read_b128 v[168:171], v176 offset:1024
	ds_read_b128 v[172:175], v176 offset:2048
	ds_read_b128 v[176:179], v176 offset:3072
	s_add_u32 s40, s40, 0x40000
	s_addc_u32 s41, s41, 0
	s_mov_b32 m0, s44
	v_lshl_add_u64 v[216:217], s[40:41], 0, v[152:153]
	ds_read_b128 v[180:183], v141 offset:32768
	ds_read_b128 v[184:187], v141 offset:33792
	ds_read_b128 v[188:191], v141 offset:34816
	ds_read_b128 v[192:195], v141 offset:35840
	ds_read_b128 v[196:199], v141 offset:36864
	ds_read_b128 v[200:203], v141 offset:37888
	ds_read_b128 v[204:207], v141 offset:38912
	ds_read_b128 v[208:211], v141 offset:39936
	global_load_lds_dwordx4 v[216:217], off
	v_lshl_add_u64 v[216:217], s[40:41], 0, v[154:155]
	s_mov_b32 m0, s45
	s_nop 0
	global_load_lds_dwordx4 v[216:217], off
	s_waitcnt vmcnt(8)
	s_waitcnt lgkmcnt(0)
	s_barrier
	s_setprio 1
	s_waitcnt lgkmcnt(0)
	v_mfma_f32_16x16x32_bf16 v[124:127], v[142:145], v[180:183], v[124:127]
	v_mfma_f32_16x16x32_bf16 v[120:123], v[156:159], v[180:183], v[120:123]
	v_mfma_f32_16x16x32_bf16 v[112:115], v[142:145], v[188:191], v[112:115]
	v_mfma_f32_16x16x32_bf16 v[108:111], v[156:159], v[188:191], v[108:111]
	v_mfma_f32_16x16x32_bf16 v[96:99], v[142:145], v[196:199], v[96:99]
	v_mfma_f32_16x16x32_bf16 v[92:95], v[156:159], v[196:199], v[92:95]
	v_mfma_f32_16x16x32_bf16 v[80:83], v[142:145], v[204:207], v[80:83]
	v_mfma_f32_16x16x32_bf16 v[76:79], v[156:159], v[204:207], v[76:79]
	v_mfma_f32_16x16x32_bf16 v[124:127], v[146:149], v[184:187], v[124:127]
	v_mfma_f32_16x16x32_bf16 v[120:123], v[160:163], v[184:187], v[120:123]
	v_mfma_f32_16x16x32_bf16 v[112:115], v[146:149], v[192:195], v[112:115]
	v_mfma_f32_16x16x32_bf16 v[108:111], v[160:163], v[192:195], v[108:111]
	v_mfma_f32_16x16x32_bf16 v[96:99], v[146:149], v[200:203], v[96:99]
	v_mfma_f32_16x16x32_bf16 v[92:95], v[160:163], v[200:203], v[92:95]
	v_mfma_f32_16x16x32_bf16 v[80:83], v[146:149], v[208:211], v[80:83]
	v_mfma_f32_16x16x32_bf16 v[76:79], v[160:163], v[208:211], v[76:79]
	s_setprio 0
	s_setprio 1
	v_mfma_f32_16x16x32_bf16 v[116:119], v[164:167], v[180:183], v[116:119]
	v_mfma_f32_16x16x32_bf16 v[104:107], v[172:175], v[180:183], v[104:107]
	v_mfma_f32_16x16x32_bf16 v[100:103], v[164:167], v[188:191], v[100:103]
	v_mfma_f32_16x16x32_bf16 v[88:91], v[172:175], v[188:191], v[88:91]
	v_mfma_f32_16x16x32_bf16 v[84:87], v[164:167], v[196:199], v[84:87]
	v_mfma_f32_16x16x32_bf16 v[72:75], v[172:175], v[196:199], v[72:75]
	v_mfma_f32_16x16x32_bf16 v[68:71], v[164:167], v[204:207], v[68:71]
	v_mfma_f32_16x16x32_bf16 v[64:67], v[172:175], v[204:207], v[64:67]
	v_mfma_f32_16x16x32_bf16 v[116:119], v[168:171], v[184:187], v[116:119]
	v_mfma_f32_16x16x32_bf16 v[104:107], v[176:179], v[184:187], v[104:107]
	v_mfma_f32_16x16x32_bf16 v[100:103], v[168:171], v[192:195], v[100:103]
	v_mfma_f32_16x16x32_bf16 v[88:91], v[176:179], v[192:195], v[88:91]
	v_mfma_f32_16x16x32_bf16 v[84:87], v[168:171], v[200:203], v[84:87]
	v_mfma_f32_16x16x32_bf16 v[72:75], v[176:179], v[200:203], v[72:75]
	v_mfma_f32_16x16x32_bf16 v[68:71], v[168:171], v[208:211], v[68:71]
	v_mfma_f32_16x16x32_bf16 v[64:67], v[176:179], v[208:211], v[64:67]
	s_setprio 0
	s_barrier
; #define PG8_STAGE(bufoff, gbase, voff) do { _Pragma("unroll") for (int _i = 0; _i < 2; ++_i) \
;         __builtin_amdgcn_global_load_lds((const unsigned*)((const char*)(gbase) + (voff)[_i]), (PG8_LAS unsigned*)(lds + (bufoff) + ldsw + _i * 8192), 16, 0, 0); } while (0)
; #define PG8_LDA(dst, b, h) do { _Pragma("unroll") for (int m = 0; m < 4; ++m) _Pragma("unroll") for (int k = 0; k < 2; ++k) dst[m][k] = *(const PG8_LAS bf16x8*)(lds + PG8_SA(b, h) + aoff + m * 2048 + k * 1024); } while (0)
; #define PG8_LDB(dst, b, h) do { _Pragma("unroll") for (int n = 0; n < 2; ++n) _Pragma("unroll") for (int k = 0; k < 2; ++k) dst[n][k] = *(const PG8_LAS bf16x8*)(lds + PG8_SB(b, h) + boff + n * 2048 + k * 1024); } while (0)
; template <class Epi, class Sched, bool ALIGN_EPI = false, bool SP2 = false>
; __device__ __forceinline__ void gemm_phase(PG8_LAS unsigned char* lds, const Gemm g, const Sched& S, const Epi& E) {
;     ...
;         for (int t = 0; t < nt; t += 2) {
;             const bool last = (t == nt - 2);
;             const char* a1 = cA + (size_t)(t + 1) * kstep;
;             const char* a2 = last ? nA : cA + (size_t)(t + 2) * kstep; const char* b2 = last ? nB : cB + (size_t)(t + 2) * kstep;
;             const char* a3 = a2 + kstep; const char* b3 = b2 + kstep;
;             if (last && has_next) S.a_ready(nxt);
;             if constexpr (SP2) {
;             PG8_LDB(B0, 0, 0); PG8_LDB(B1, 0, 1); PG8_SCHED; PG8_LDA(At, 0, 0); PG8_STAGE(PG8_SA(1, 1), a1 + hstep, voffA);
;             PG8_WAIT_V(8); PG8_WAIT_L(0); PG8_BAR; PG8_MMA(0, 0, At, B0); PG8_MMA(0, 1, At, B1); PG8_BAR; PG8_SCHED;
;             PG8_LDA(At, 0, 1); PG8_STAGE(PG8_SB(0, 0), b2, voffB); PG8_STAGE(PG8_SB(0, 1), b2 + hstepB, voffB); PG8_STAGE(PG8_SA(0, 0), a2, voffA);
;             PG8_WAIT_V(8); PG8_WAIT_L(0); PG8_BAR; PG8_MMA(1, 0, At, B0); PG8_MMA(1, 1, At, B1); PG8_BAR; PG8_SCHED;
;             PG8_LDB(B0, 1, 0); PG8_LDB(B1, 1, 1); PG8_SCHED; PG8_LDA(At, 1, 0); PG8_STAGE(PG8_SA(0, 1), a2 + hstep, voffA);
;             PG8_WAIT_V(8); PG8_WAIT_L(0); PG8_BAR; PG8_MMA(0, 0, At, B0); PG8_MMA(0, 1, At, B1); PG8_BAR; PG8_SCHED;
;             PG8_LDA(At, 1, 1); PG8_STAGE(PG8_SB(1, 0), b3, voffB); PG8_STAGE(PG8_SB(1, 1), b3 + hstepB, voffB); PG8_STAGE(PG8_SA(1, 0), a3, voffA);
;             PG8_WAIT_V(8); PG8_WAIT_L(0); PG8_BAR; PG8_MMA(1, 0, At, B0); PG8_MMA(1, 1, At, B1); PG8_BAR; PG8_SCHED;
	s_add_i32 s40, s61, s42
	v_lshl_add_u64 v[134:135], v[134:135], 0, s[4:5]
	s_mov_b32 m0, s40
	ds_read_b128 v[180:183], v141 offset:49152
	ds_read_b128 v[184:187], v141 offset:50176
	ds_read_b128 v[188:191], v141 offset:51200
	ds_read_b128 v[192:195], v141 offset:52224
	ds_read_b128 v[196:199], v141 offset:53248
	ds_read_b128 v[200:203], v141 offset:54272
	ds_read_b128 v[204:207], v141 offset:55296
	ds_read_b128 v[208:211], v141 offset:56320
	global_load_lds_dwordx4 v[134:135], off
	s_add_i32 m0, s40, 0x2000
	s_add_u32 s34, s34, 0x40080
	v_lshl_add_u64 v[134:135], v[150:151], 0, s[4:5]
	s_addc_u32 s35, s35, 0
	s_add_i32 s40, s62, s42
	global_load_lds_dwordx4 v[134:135], off
	v_lshl_add_u64 v[134:135], s[34:35], 0, v[152:153]
	s_mov_b32 m0, s40
	s_nop 0
	global_load_lds_dwordx4 v[134:135], off
	v_lshl_add_u64 v[134:135], s[34:35], 0, v[154:155]
	s_add_i32 m0, s40, 0x2000
	s_nop 0
	global_load_lds_dwordx4 v[134:135], off
	v_lshl_add_u64 v[134:135], v[212:213], 0, s[4:5]
	s_mov_b32 m0, s47
	s_nop 0
	global_load_lds_dwordx4 v[134:135], off
	v_lshl_add_u64 v[134:135], v[214:215], 0, s[4:5]
	s_mov_b32 m0, s48
	s_nop 0
	global_load_lds_dwordx4 v[134:135], off
	s_waitcnt vmcnt(8)
	s_waitcnt lgkmcnt(0)
	s_barrier
	s_setprio 1
	s_waitcnt lgkmcnt(0)
	v_mfma_f32_16x16x32_bf16 v[60:63], v[142:145], v[180:183], v[60:63]
	v_mfma_f32_16x16x32_bf16 v[56:59], v[156:159], v[180:183], v[56:59]
	v_mfma_f32_16x16x32_bf16 v[48:51], v[142:145], v[188:191], v[48:51]
	v_mfma_f32_16x16x32_bf16 v[44:47], v[156:159], v[188:191], v[44:47]
	v_mfma_f32_16x16x32_bf16 v[32:35], v[142:145], v[196:199], v[32:35]
	v_mfma_f32_16x16x32_bf16 v[28:31], v[156:159], v[196:199], v[28:31]
	v_mfma_f32_16x16x32_bf16 v[16:19], v[142:145], v[204:207], v[16:19]
	v_mfma_f32_16x16x32_bf16 v[12:15], v[156:159], v[204:207], v[12:15]
	v_mfma_f32_16x16x32_bf16 v[60:63], v[146:149], v[184:187], v[60:63]
	v_mfma_f32_16x16x32_bf16 v[56:59], v[160:163], v[184:187], v[56:59]
	v_mfma_f32_16x16x32_bf16 v[48:51], v[146:149], v[192:195], v[48:51]
	v_mfma_f32_16x16x32_bf16 v[44:47], v[160:163], v[192:195], v[44:47]
	v_mfma_f32_16x16x32_bf16 v[32:35], v[146:149], v[200:203], v[32:35]
	v_mfma_f32_16x16x32_bf16 v[28:31], v[160:163], v[200:203], v[28:31]
	v_mfma_f32_16x16x32_bf16 v[16:19], v[146:149], v[208:211], v[16:19]
	v_mfma_f32_16x16x32_bf16 v[12:15], v[160:163], v[208:211], v[12:15]
	s_setprio 0
	s_setprio 1
	v_mfma_f32_16x16x32_bf16 v[52:55], v[164:167], v[180:183], v[52:55]
	v_mfma_f32_16x16x32_bf16 v[40:43], v[172:175], v[180:183], v[40:43]
	v_mfma_f32_16x16x32_bf16 v[36:39], v[164:167], v[188:191], v[36:39]
	v_mfma_f32_16x16x32_bf16 v[24:27], v[172:175], v[188:191], v[24:27]
	v_mfma_f32_16x16x32_bf16 v[20:23], v[164:167], v[196:199], v[20:23]
	v_mfma_f32_16x16x32_bf16 v[8:11], v[172:175], v[196:199], v[8:11]
	v_mfma_f32_16x16x32_bf16 v[4:7], v[164:167], v[204:207], v[4:7]
	v_mfma_f32_16x16x32_bf16 v[0:3], v[172:175], v[204:207], v[0:3]
	v_mfma_f32_16x16x32_bf16 v[52:55], v[168:171], v[184:187], v[52:55]
	v_mfma_f32_16x16x32_bf16 v[40:43], v[176:179], v[184:187], v[40:43]
	v_mfma_f32_16x16x32_bf16 v[36:39], v[168:171], v[192:195], v[36:39]
	v_mfma_f32_16x16x32_bf16 v[24:27], v[176:179], v[192:195], v[24:27]
	v_mfma_f32_16x16x32_bf16 v[20:23], v[168:171], v[200:203], v[20:23]
	v_mfma_f32_16x16x32_bf16 v[8:11], v[176:179], v[200:203], v[8:11]
	v_mfma_f32_16x16x32_bf16 v[4:7], v[168:171], v[208:211], v[4:7]
	v_mfma_f32_16x16x32_bf16 v[0:3], v[176:179], v[208:211], v[0:3]
	s_setprio 0
	s_barrier
	s_add_i32 s60, s60, 2
	s_mov_b32 s99, 0
	s_add_u32 s28, s28, 0x100
	s_addc_u32 s29, s29, 0
	s_add_u32 s58, s58, 0x100
	s_addc_u32 s59, s59, 0
	s_cmp_gt_u32 s60, 13
	s_cbranch_scc0 .LBB0_478
	s_and_b64 vcc, exec, s[6:7]
	s_cbranch_vccz .LBB0_481
	s_barrier

; #define LAS __attribute__((address_space(3)))
; __global__ void __launch_bounds__(512, 2) mega_fwd(Args a) {
;     extern __shared__ __attribute__((aligned(16))) unsigned char lds_raw[];
;     LAS unsigned char* lds = (LAS unsigned char*)lds_raw;
;     cg::grid_group grid = cg::this_grid();
;     const int tid = threadIdx.x, lane = tid & 63, wave = __builtin_amdgcn_readfirstlane(tid >> 6);
	.amdhsa_kernel _Z8mega_fwd4Args
		.amdhsa_group_segment_fixed_size 0
		.amdhsa_private_segment_fixed_size 0
		.amdhsa_kernarg_size 328
		.amdhsa_user_sgpr_count 2
		.amdhsa_user_sgpr_dispatch_ptr 0
		.amdhsa_user_sgpr_queue_ptr 0
		.amdhsa_user_sgpr_kernarg_segment_ptr 1
		.amdhsa_user_sgpr_dispatch_id 0
		.amdhsa_user_sgpr_kernarg_preload_length 0
		.amdhsa_user_sgpr_kernarg_preload_offset 0
		.amdhsa_user_sgpr_private_segment_size 0
		.amdhsa_uses_dynamic_stack 0
		.amdhsa_enable_private_segment 0
		.amdhsa_system_sgpr_workgroup_id_x 1
		.amdhsa_system_sgpr_workgroup_id_y 0
		.amdhsa_system_sgpr_workgroup_id_z 0
		.amdhsa_system_sgpr_workgroup_info 0
		.amdhsa_system_vgpr_workitem_id 2
		.amdhsa_next_free_vgpr 243
		.amdhsa_next_free_sgpr 100
		.amdhsa_accum_offset 244
		.amdhsa_reserve_vcc 1
		.amdhsa_float_round_mode_32 0
		.amdhsa_float_round_mode_16_64 0
		.amdhsa_float_denorm_mode_32 3
		.amdhsa_float_denorm_mode_16_64 3
		.amdhsa_dx10_clamp 1
		.amdhsa_ieee_mode 1
		.amdhsa_fp16_overflow 0
		.amdhsa_tg_split 0
		.amdhsa_exception_fp_ieee_invalid_op 0
		.amdhsa_exception_fp_denorm_src 0
		.amdhsa_exception_fp_ieee_div_zero 0
		.amdhsa_exception_fp_ieee_overflow 0
		.amdhsa_exception_fp_ieee_underflow 0
		.amdhsa_exception_fp_ieee_inexact 0
		.amdhsa_exception_int_div_zero 0
	.end_amdhsa_kernel

; #define LAS __attribute__((address_space(3)))
; __global__ void __launch_bounds__(512, 2) mega_fwd(Args a) {
;     extern __shared__ __attribute__((aligned(16))) unsigned char lds_raw[];
;     LAS unsigned char* lds = (LAS unsigned char*)lds_raw;
;     cg::grid_group grid = cg::this_grid();
;     const int tid = threadIdx.x, lane = tid & 63, wave = __builtin_amdgcn_readfirstlane(tid >> 6);
amdhsa.kernels:
  - .agpr_count:     0
    .args:
      - .offset:         0
        .size:           72
        .value_kind:     by_value
      - .offset:         72
        .size:           4
        .value_kind:     hidden_block_count_x
      - .offset:         76
        .size:           4
        .value_kind:     hidden_block_count_y
      - .offset:         80
        .size:           4
        .value_kind:     hidden_block_count_z
      - .offset:         84
        .size:           2
        .value_kind:     hidden_group_size_x
      - .offset:         86
        .size:           2
        .value_kind:     hidden_group_size_y
      - .offset:         88
        .size:           2
        .value_kind:     hidden_group_size_z
      - .offset:         90
        .size:           2
        .value_kind:     hidden_remainder_x
      - .offset:         92
        .size:           2
        .value_kind:     hidden_remainder_y
      - .offset:         94
        .size:           2
        .value_kind:     hidden_remainder_z
      - .offset:         112
        .size:           8
        .value_kind:     hidden_global_offset_x
      - .offset:         120
        .size:           8
        .value_kind:     hidden_global_offset_y
      - .offset:         128
        .size:           8
        .value_kind:     hidden_global_offset_z
      - .offset:         136
        .size:           2
        .value_kind:     hidden_grid_dims
      - .offset:         160
        .size:           8
        .value_kind:     hidden_multigrid_sync_arg
      - .offset:         192
        .size:           4
        .value_kind:     hidden_dynamic_lds_size
    .group_segment_fixed_size: 0
    .kernarg_segment_align: 8
    .kernarg_segment_size: 328
    .language:       OpenCL C
    .language_version:
      - 2
      - 0
    .max_flat_workgroup_size: 512
    .name:           _Z8mega_fwd4Args
    .private_segment_fixed_size: 0
    .sgpr_count:     106
    .sgpr_spill_count: 0
    .symbol:         _Z8mega_fwd4Args.kd
    .uniform_work_group_size: 1
    .uses_dynamic_stack: false
    .vgpr_count:     243
    .vgpr_spill_count: 0
    .wavefront_size: 64
